# fused diff attention v4: V fragment reads ride in the QK MFMA gaps, exp/row-sum/pack of key group g+1 ride in the P.V MFMA gaps of group g, 4-slot rings, masked wave-tiles skipped
# speedup vs baseline: 1.0489x; 1.0103x over previous
;   #define DMA_K(t,slot) glds16(ksrc+(long)(t)*KVBLK*KP,(unsigned)__builtin_amdgcn_readfirstlane(kdst+(slot)))
;   #define DMA_V(t,slot) glds16(vsrc+(long)(t)*KVBLK*VP,(unsigned)__builtin_amdgcn_readfirstlane(vdst+(slot)))
;   int tidv; asm volatile("v_mbcnt_lo_u32_b32 %0, -1, 0\n\tv_mbcnt_hi_u32_b32 %0, -1, %0":"=v"(tidv)); tidv+=wave_*64;
;   const int tid=tidv,lane=tid&63,r32=lane&31,hi=lane>>5; const int wid=__builtin_amdgcn_readfirstlane(tid>>6);
;   const int q0=qb*QB;
;   const bf16*Qw=Qb+(long)(wid*QBLK)*QP;
;   const unsigned lds0=(unsigned)(uintptr_t)shm;
;   float*wsf=(float*)(shm+LDS_WS)+wid*64;
;   const bf16*ksrc=Kh+(long)lane*KP+wid*8;
;   const bf16*vsrc=Vh+(long)(16*(wid&3)+(lane>>2))*VP+(wid>>2)*32+(lane&3)*8;
;   const unsigned kdst=lds0+LDS_K+wid*1024, vdst=lds0+LDS_V+wid*1024;
;     ...
;   const int vb0=(int)(lds0+LDS_V)+((lane>>4)&1)*32+(lane&3)*8+(4*hi+((lane&15)>>2))*64;
;   const char*Kbase=shm+LDS_K; bf16x8 kf[8];
;   const lds_cptr shm3=(lds_cptr)shm; const lds_cptr kp0=shm3+LDS_K+hi*1024+r32*16; const lds_cptr vp0=shm3+LDS_V+((lane>>4)&1)*32+(lane&3)*8+(4*hi+((lane&15)>>2))*64;
;   const int NT=(q0+QB)/KVBLK;
;   const __attribute__((address_space(3))) unsigned* mimg=(const __attribute__((address_space(3))) unsigned*)(shm3+LDS_OST+wid*MWAVE)+r32;
;   DMA_K(0,0);DMA_V(0,0);DMA_K(1,SLOTB);
;   if constexpr(MASKED){
;     __attribute__((address_space(3))) u32x4* mdst=(__attribute__((address_space(3))) u32x4*)(shm3+LDS_OST+wid*MWAVE)+lane;
;     for(int i=0;i<=qb;++i){ const u32x4 v=((const u32x4*)mwave)[i*64+lane]; mdst[i*64]=v; }
;   }
;   bf16x8 qr[4];
;   #pragma unroll
;   for(int d0=0;d0<4;++d0)qr[d0]=*reinterpret_cast<const bf16x8*>(&Qw[(long)r32*QP+d0*16+hi*8]);
;   float mhat=0.f,l_reg=0.f;f32x16 o[2];o[0]=f32x16{};o[1]=f32x16{};f32x16 negm=f32x16{};asm volatile("":"+v"(negm));
;   const int qrel=wid*QBLK+r32;
; __device__ __forceinline__ void run(Frame& F, int qword) {
;     ...
;             for (int sp = 0; sp < 4; ++sp) {
;                 const int c = sp >> 1, vh = sp & 1;
;                 attn_body::attn_unit<8, false>(qb, QB + rq * 512 + (h * 2 + c) * 64, 512, KB + r0 * 512 + (h * 2 + c) * 64, 512, VB + r0 * 512 + h * 128 + vh * 64, 512,
;                                                ATT + rq * 1024 + 512 + h * 128, 1024, nullptr, shm, F.wave, sp < 2 ? 1 : (sp == 2 ? 2 : 3), vh, lam);
.Lfd_entry:
	v_readlane_b32 s8, v254, 11
	v_mbcnt_lo_u32_b32 v0, -1, 0
	v_mbcnt_hi_u32_b32 v0, -1, v0
	v_and_b32_e32 v2, 31, v0
	v_lshrrev_b32_e32 v3, 5, v0
	s_lshl_b32 s89, s79, 2
	s_add_i32 s89, s89, 4
	s_lshl_b32 s0, s8, 4
	v_lshlrev_b32_e32 v10, 10, v0
	v_add_u32_e32 v10, s0, v10
	s_and_b32 s0, s8, 3
	s_lshl_b32 s0, s0, 14
	s_lshr_b32 s1, s8, 2
	s_lshl_b32 s1, s1, 6
	s_add_i32 s0, s0, s1
	v_lshrrev_b32_e32 v4, 2, v0
	v_lshlrev_b32_e32 v4, 10, v4
	v_and_b32_e32 v5, 3, v0
	v_lshlrev_b32_e32 v5, 4, v5
	v_add3_u32 v11, v4, v5, s0
	v_add_u32_e32 v12, 0x80, v11
	v_lshlrev_b32_e32 v13, 10, v3
	v_lshl_add_u32 v13, v2, 4, v13
	v_bfe_u32 v4, v0, 4, 1
	v_lshlrev_b32_e32 v4, 5, v4
	v_and_b32_e32 v5, 3, v0
	v_lshl_add_u32 v4, v5, 3, v4
	v_bfe_u32 v5, v0, 2, 2
	v_lshl_add_u32 v5, v3, 2, v5
	v_lshl_add_u32 v15, v5, 6, v4
	v_add_u32_e32 v15, 0x8000, v15
	s_lshl_b32 s0, s8, 8
	s_add_i32 s0, s0, 0x18000
	v_lshl_add_u32 v44, v2, 2, s0
	v_lshl_add_u32 v45, v3, 4, s0
	s_lshl_b32 s0, s8, 13
	v_lshl_add_u32 v46, v3, 10, s0
	v_lshl_add_u32 v46, v2, 1, v46
	v_lshl_add_u32 v219, v0, 4, s0
	v_lshrrev_b32_e32 v4, 4, v0
	v_and_b32_e32 v5, 15, v0
	v_lshlrev_b32_e32 v5, 4, v5
	v_lshl_add_u32 v252, v4, 11, v5
	v_lshlrev_b32_e32 v39, 10, v2
	v_lshl_add_u32 v39, v3, 4, v39
	s_lshl_b32 s0, s8, 5
	s_add_i32 s0, s0, s78
	v_add_u32_e32 v33, s0, v2
	v_lshlrev_b32_e32 v4, 2, v3
	v_sub_u32_e32 v33, v33, v4
	s_lshl_b32 s0, s8, 5
	s_add_i32 s0, s0, s26
	s_lshl_b32 s1, s28, 8
	s_add_i32 s1, s1, 0x400
	s_mov_b32 s3, 0
	s_mov_b32 s2, s0
	s_lshl_b64 s[2:3], s[2:3], 11
	s_add_u32 s2, s2, s1
	s_addc_u32 s3, s3, 0
	s_add_u32 s86, s66, s2
	s_addc_u32 s87, s67, s3
	s_lshl_b32 s22, s8, 5
	s_add_i32 s22, s22, s78
	s_add_i32 s23, s22, 31
	s_lshl_b32 s29, s8, 10
	s_mov_b32 s90, 0
.Lfd_pass:
	s_lshl_b32 s0, s28, 1
	s_add_i32 s0, s0, s90
	s_lshl_b32 s0, s0, 7
	s_mov_b32 s3, 0
	s_mov_b32 s2, s30
	s_lshl_b64 s[2:3], s[2:3], 21
	s_add_u32 s80, s62, s2
	s_addc_u32 s81, s63, s3
	s_add_u32 s80, s80, s0
	s_addc_u32 s81, s81, 0
	s_lshl_b32 s1, s28, 8
	s_add_u32 s82, s64, s2
	s_addc_u32 s83, s65, s3
	s_add_u32 s82, s82, s1
	s_addc_u32 s83, s83, 0
	s_lshl_b32 s1, s8, 5
	s_add_i32 s1, s1, s26
	s_mov_b32 s3, 0
	s_mov_b32 s2, s1
	s_lshl_b64 s[2:3], s[2:3], 10
	s_add_u32 s84, s60, s2
	s_addc_u32 s85, s61, s3
	s_add_u32 s84, s84, s0
	s_addc_u32 s85, s85, 0
	global_load_dwordx4 v[160:163], v39, s[84:85] offset:0
	global_load_dwordx4 v[164:167], v39, s[84:85] offset:32
	global_load_dwordx4 v[168:171], v39, s[84:85] offset:64
	global_load_dwordx4 v[172:175], v39, s[84:85] offset:96
	s_mov_b32 s94, 0
	s_lshl_b32 s0, s94, 16
	s_add_u32 s44, s80, s0
	s_addc_u32 s45, s81, 0
	s_add_u32 s46, s82, s0
	s_addc_u32 s47, s83, 0
	s_and_b32 s1, s94, 3
	s_lshl_b32 s1, s1, 13
	s_lshl_b32 s2, s1, 1
	s_add_i32 s1, s1, s29
	s_mov_b32 m0, s1
	s_add_i32 s2, s2, s29
	global_load_lds_dwordx4 v10, s[44:45]
	s_add_i32 s2, s2, 0x8000
	s_mov_b32 m0, s2
	s_add_i32 s2, s2, 0x2000
	global_load_lds_dwordx4 v11, s[46:47]
	s_mov_b32 m0, s2
	s_nop 0
	global_load_lds_dwordx4 v12, s[46:47]
	s_mov_b32 s94, 1
	s_lshl_b32 s0, s94, 16
	s_add_u32 s44, s80, s0
	s_addc_u32 s45, s81, 0
	s_add_u32 s46, s82, s0
	s_addc_u32 s47, s83, 0
	s_and_b32 s1, s94, 3
	s_lshl_b32 s1, s1, 13
	s_lshl_b32 s2, s1, 1
	s_add_i32 s1, s1, s29
	s_mov_b32 m0, s1
	s_add_i32 s2, s2, s29
	global_load_lds_dwordx4 v10, s[44:45]
	s_add_i32 s2, s2, 0x8000
	s_mov_b32 m0, s2
	s_add_i32 s2, s2, 0x2000
	global_load_lds_dwordx4 v11, s[46:47]
	s_mov_b32 m0, s2
	s_nop 0
	global_load_lds_dwordx4 v12, s[46:47]
	s_mov_b32 s94, 2
	s_lshl_b32 s0, s94, 16
	s_add_u32 s44, s80, s0
	s_addc_u32 s45, s81, 0
	s_add_u32 s46, s82, s0
	s_addc_u32 s47, s83, 0
	s_and_b32 s1, s94, 3
	s_lshl_b32 s1, s1, 13
	s_lshl_b32 s2, s1, 1
	s_add_i32 s1, s1, s29
	s_mov_b32 m0, s1
	s_add_i32 s2, s2, s29
	global_load_lds_dwordx4 v10, s[44:45]
	s_add_i32 s2, s2, 0x8000
	s_mov_b32 m0, s2
	s_add_i32 s2, s2, 0x2000
	global_load_lds_dwordx4 v11, s[46:47]
	s_mov_b32 m0, s2
	s_nop 0
	global_load_lds_dwordx4 v12, s[46:47]
	v_mov_b32_e32 v48, 0
	v_mov_b32_e32 v49, 0
	v_mov_b32_e32 v50, 0
	v_mov_b32_e32 v51, 0
	v_mov_b32_e32 v52, 0
	v_mov_b32_e32 v53, 0
	v_mov_b32_e32 v54, 0
	v_mov_b32_e32 v55, 0
	v_mov_b32_e32 v56, 0
	v_mov_b32_e32 v57, 0
	v_mov_b32_e32 v58, 0
	v_mov_b32_e32 v59, 0
	v_mov_b32_e32 v60, 0
	v_mov_b32_e32 v61, 0
	v_mov_b32_e32 v62, 0
	v_mov_b32_e32 v63, 0
	v_mov_b32_e32 v64, 0
	v_mov_b32_e32 v65, 0
	v_mov_b32_e32 v66, 0
	v_mov_b32_e32 v67, 0
	v_mov_b32_e32 v68, 0
	v_mov_b32_e32 v69, 0
	v_mov_b32_e32 v70, 0
	v_mov_b32_e32 v71, 0
	v_mov_b32_e32 v72, 0
	v_mov_b32_e32 v73, 0
	v_mov_b32_e32 v74, 0
	v_mov_b32_e32 v75, 0
	v_mov_b32_e32 v76, 0
	v_mov_b32_e32 v77, 0
	v_mov_b32_e32 v78, 0
	v_mov_b32_e32 v79, 0
	v_mov_b32_e32 v80, 0
	v_mov_b32_e32 v81, 0
	v_mov_b32_e32 v82, 0
	v_mov_b32_e32 v83, 0
	v_mov_b32_e32 v84, 0
	v_mov_b32_e32 v85, 0
	v_mov_b32_e32 v86, 0
	v_mov_b32_e32 v87, 0
	v_mov_b32_e32 v88, 0
	v_mov_b32_e32 v89, 0
	v_mov_b32_e32 v90, 0
	v_mov_b32_e32 v91, 0
	v_mov_b32_e32 v92, 0
	v_mov_b32_e32 v93, 0
	v_mov_b32_e32 v94, 0
	v_mov_b32_e32 v95, 0
	v_mov_b32_e32 v96, 0
	v_mov_b32_e32 v97, 0
	v_mov_b32_e32 v98, 0
	v_mov_b32_e32 v99, 0
	v_mov_b32_e32 v100, 0
	v_mov_b32_e32 v101, 0
	v_mov_b32_e32 v102, 0
	v_mov_b32_e32 v103, 0
	v_mov_b32_e32 v104, 0
	v_mov_b32_e32 v105, 0
	v_mov_b32_e32 v106, 0
	v_mov_b32_e32 v107, 0
	v_mov_b32_e32 v108, 0
	v_mov_b32_e32 v109, 0
	v_mov_b32_e32 v110, 0
	v_mov_b32_e32 v111, 0
	v_mov_b32_e32 v144, 0
	v_mov_b32_e32 v145, 0
	v_mov_b32_e32 v146, 0
	v_mov_b32_e32 v147, 0
	v_mov_b32_e32 v148, 0
	v_mov_b32_e32 v149, 0
	v_mov_b32_e32 v150, 0
	v_mov_b32_e32 v151, 0
	v_mov_b32_e32 v152, 0
	v_mov_b32_e32 v153, 0
	v_mov_b32_e32 v154, 0
	v_mov_b32_e32 v155, 0
	v_mov_b32_e32 v156, 0
	v_mov_b32_e32 v157, 0
	v_mov_b32_e32 v158, 0
	v_mov_b32_e32 v159, 0
	v_mov_b32_e32 v34, 0
	v_mov_b32_e32 v35, 0
	s_mov_b32 s88, 0
	s_waitcnt vmcnt(6)
	s_barrier
; __device__ __forceinline__ void cmask(f32x16&p0,f32x16&p1,int jb,int qrel,int hi,int wrow){
;   const float NEG=-INFINITY; int kb=64*jb+4*hi;
;   if(64*jb+63<=wrow) return;
;   if(64*jb>wrow+31){
;     #pragma unroll
;     for(int r=0;r<16;++r){p0[r]=NEG;p1[r]=NEG;}
;     return; }
;   #pragma unroll
;   for(int r=0;r<16;++r){int kv=kb+(r&3)+8*(r>>2); if(kv>qrel)p0[r]=NEG; if(kv+32>qrel)p1[r]=NEG;}
; }
.Lfd_loop:
	s_waitcnt vmcnt(3)
	s_barrier
	s_add_i32 s94, s88, 3
	s_add_i32 s0, s89, -1
	s_min_i32 s94, s94, s0
	s_lshl_b32 s0, s94, 16
	s_add_u32 s44, s80, s0
	s_addc_u32 s45, s81, 0
	s_add_u32 s46, s82, s0
	s_addc_u32 s47, s83, 0
	s_and_b32 s1, s94, 3
	s_lshl_b32 s1, s1, 13
	s_lshl_b32 s2, s1, 1
	s_add_i32 s1, s1, s29
	s_mov_b32 m0, s1
	s_add_i32 s2, s2, s29
	global_load_lds_dwordx4 v10, s[44:45]
	s_add_i32 s2, s2, 0x8000
	s_mov_b32 m0, s2
	s_add_i32 s2, s2, 0x2000
	global_load_lds_dwordx4 v11, s[46:47]
	s_mov_b32 m0, s2
	s_nop 0
	global_load_lds_dwordx4 v12, s[46:47]
	s_lshl_b32 s0, s88, 6
	s_cmp_gt_i32 s0, s23
	s_cbranch_scc1 .Lfd_next
	s_and_b32 s0, s88, 3
	s_lshl_b32 s0, s0, 13
	v_add_u32_e32 v14, s0, v13
	ds_read_b128 v[176:179], v14 offset:0
	ds_read_b128 v[180:183], v14 offset:512
	ds_read_b128 v[184:187], v14 offset:2048
	ds_read_b128 v[188:191], v14 offset:2560
	ds_read_b128 v[192:195], v14 offset:4096
	ds_read_b128 v[196:199], v14 offset:4608
	ds_read_b128 v[200:203], v14 offset:6144
	ds_read_b128 v[204:207], v14 offset:6656
	s_and_b32 s0, s88, 3
	s_lshl_b32 s0, s0, 14
	v_add_u32_e32 v32, s0, v15
	s_waitcnt lgkmcnt(6)
	v_mfma_f32_32x32x16_bf16 v[112:127], v[176:179], v[160:163], v[144:159]
	ds_read_b64_tr_b16 v[220:221], v32 offset:8192
	ds_read_b64_tr_b16 v[222:223], v32 offset:8704
	v_mfma_f32_32x32x16_bf16 v[128:143], v[180:183], v[160:163], v[144:159]
	ds_read_b64_tr_b16 v[224:225], v32 offset:9216
	ds_read_b64_tr_b16 v[226:227], v32 offset:9728
	s_waitcnt lgkmcnt(8)
	v_mfma_f32_32x32x16_bf16 v[112:127], v[184:187], v[164:167], v[112:127]
	ds_read_b64_tr_b16 v[228:229], v32 offset:10240
	ds_read_b64_tr_b16 v[230:231], v32 offset:10752
	v_mfma_f32_32x32x16_bf16 v[128:143], v[188:191], v[164:167], v[128:143]
	ds_read_b64_tr_b16 v[232:233], v32 offset:11264
	ds_read_b64_tr_b16 v[234:235], v32 offset:11776
	s_waitcnt lgkmcnt(10)
	v_mfma_f32_32x32x16_bf16 v[112:127], v[192:195], v[168:171], v[112:127]
	ds_read_b64_tr_b16 v[236:237], v32 offset:12288
	ds_read_b64_tr_b16 v[238:239], v32 offset:12800
	v_mfma_f32_32x32x16_bf16 v[128:143], v[196:199], v[168:171], v[128:143]
	ds_read_b64_tr_b16 v[240:241], v32 offset:13312
	ds_read_b64_tr_b16 v[242:243], v32 offset:13824
	s_waitcnt lgkmcnt(12)
	v_mfma_f32_32x32x16_bf16 v[112:127], v[200:203], v[172:175], v[112:127]
	ds_read_b64_tr_b16 v[244:245], v32 offset:14336
	ds_read_b64_tr_b16 v[246:247], v32 offset:14848
	v_mfma_f32_32x32x16_bf16 v[128:143], v[204:207], v[172:175], v[128:143]
	ds_read_b64_tr_b16 v[248:249], v32 offset:15360
	ds_read_b64_tr_b16 v[250:251], v32 offset:15872
	ds_read_b64_tr_b16 v[176:177], v32 offset:0
	ds_read_b64_tr_b16 v[178:179], v32 offset:512
	ds_read_b64_tr_b16 v[180:181], v32 offset:1024
	ds_read_b64_tr_b16 v[182:183], v32 offset:1536
	ds_read_b64_tr_b16 v[184:185], v32 offset:2048
	ds_read_b64_tr_b16 v[186:187], v32 offset:2560
	ds_read_b64_tr_b16 v[188:189], v32 offset:3072
	ds_read_b64_tr_b16 v[190:191], v32 offset:3584
	ds_read_b64_tr_b16 v[192:193], v32 offset:4096
	ds_read_b64_tr_b16 v[194:195], v32 offset:4608
	ds_read_b64_tr_b16 v[196:197], v32 offset:5120
	ds_read_b64_tr_b16 v[198:199], v32 offset:5632
	ds_read_b64_tr_b16 v[200:201], v32 offset:6144
	ds_read_b64_tr_b16 v[202:203], v32 offset:6656
	ds_read_b64_tr_b16 v[204:205], v32 offset:7168
	ds_read_b64_tr_b16 v[206:207], v32 offset:7680
	s_lshl_b32 s0, s88, 6
	s_add_i32 s1, s0, 63
	s_cmp_le_i32 s1, s22
	s_cbranch_scc1 .Lfd_nomaskA
	v_subrev_u32_e32 v4, s0, v33
	v_cmp_gt_i32_e64 s[36:37], 0, v4
	v_cmp_gt_i32_e64 s[38:39], 1, v4
	v_cmp_gt_i32_e64 s[48:49], 2, v4
	v_cmp_gt_i32_e64 s[50:51], 3, v4
	v_cndmask_b32_e64 v112, v112, v47, s[36:37]
	v_cndmask_b32_e64 v113, v113, v47, s[38:39]
	v_cndmask_b32_e64 v114, v114, v47, s[48:49]
	v_cndmask_b32_e64 v115, v115, v47, s[50:51]
	v_cmp_gt_i32_e64 s[36:37], 8, v4
	v_cmp_gt_i32_e64 s[38:39], 9, v4
	v_cmp_gt_i32_e64 s[48:49], 10, v4
	v_cmp_gt_i32_e64 s[50:51], 11, v4
	v_cndmask_b32_e64 v116, v116, v47, s[36:37]
	v_cndmask_b32_e64 v117, v117, v47, s[38:39]
	v_cndmask_b32_e64 v118, v118, v47, s[48:49]
	v_cndmask_b32_e64 v119, v119, v47, s[50:51]
	v_cmp_gt_i32_e64 s[36:37], 16, v4
	v_cmp_gt_i32_e64 s[38:39], 17, v4
	v_cmp_gt_i32_e64 s[48:49], 18, v4
	v_cmp_gt_i32_e64 s[50:51], 19, v4
	v_cndmask_b32_e64 v120, v120, v47, s[36:37]
	v_cndmask_b32_e64 v121, v121, v47, s[38:39]
	v_cndmask_b32_e64 v122, v122, v47, s[48:49]
	v_cndmask_b32_e64 v123, v123, v47, s[50:51]
	v_cmp_gt_i32_e64 s[36:37], 24, v4
	v_cmp_gt_i32_e64 s[38:39], 25, v4
	v_cmp_gt_i32_e64 s[48:49], 26, v4
	v_cmp_gt_i32_e64 s[50:51], 27, v4
	v_cndmask_b32_e64 v124, v124, v47, s[36:37]
	v_cndmask_b32_e64 v125, v125, v47, s[38:39]
	v_cndmask_b32_e64 v126, v126, v47, s[48:49]
	v_cndmask_b32_e64 v127, v127, v47, s[50:51]
	v_cmp_gt_i32_e64 s[36:37], 32, v4
	v_cmp_gt_i32_e64 s[38:39], 33, v4
	v_cmp_gt_i32_e64 s[48:49], 34, v4
	v_cmp_gt_i32_e64 s[50:51], 35, v4
	v_cndmask_b32_e64 v128, v128, v47, s[36:37]
	v_cndmask_b32_e64 v129, v129, v47, s[38:39]
	v_cndmask_b32_e64 v130, v130, v47, s[48:49]
	v_cndmask_b32_e64 v131, v131, v47, s[50:51]
	v_cmp_gt_i32_e64 s[36:37], 40, v4
	v_cmp_gt_i32_e64 s[38:39], 41, v4
	v_cmp_gt_i32_e64 s[48:49], 42, v4
	v_cmp_gt_i32_e64 s[50:51], 43, v4
	v_cndmask_b32_e64 v132, v132, v47, s[36:37]
	v_cndmask_b32_e64 v133, v133, v47, s[38:39]
	v_cndmask_b32_e64 v134, v134, v47, s[48:49]
	v_cndmask_b32_e64 v135, v135, v47, s[50:51]
	v_cmp_gt_i32_e64 s[36:37], 48, v4
	v_cmp_gt_i32_e64 s[38:39], 49, v4
	v_cmp_gt_i32_e64 s[48:49], 50, v4
	v_cmp_gt_i32_e64 s[50:51], 51, v4
	v_cndmask_b32_e64 v136, v136, v47, s[36:37]
	v_cndmask_b32_e64 v137, v137, v47, s[38:39]
	v_cndmask_b32_e64 v138, v138, v47, s[48:49]
	v_cndmask_b32_e64 v139, v139, v47, s[50:51]
	v_cmp_gt_i32_e64 s[36:37], 56, v4
	v_cmp_gt_i32_e64 s[38:39], 57, v4
	v_cmp_gt_i32_e64 s[48:49], 58, v4
	v_cmp_gt_i32_e64 s[50:51], 59, v4
	v_cndmask_b32_e64 v140, v140, v47, s[36:37]
	v_cndmask_b32_e64 v141, v141, v47, s[38:39]
	v_cndmask_b32_e64 v142, v142, v47, s[48:49]
	v_cndmask_b32_e64 v143, v143, v47, s[50:51]
.Lfd_nomaskA:
	s_and_b32 s0, s88, 1
	s_cmp_lg_u32 s0, 0
	s_cbranch_scc1 .Lfd_norescA
	v_max3_f32 v36, v112, v113, v114
	v_max3_f32 v37, v128, v129, v130
	v_max3_f32 v36, v36, v115, v116
	v_max3_f32 v37, v37, v117, v118
	v_max3_f32 v36, v36, v119, v120
	v_max3_f32 v37, v37, v121, v122
	v_max3_f32 v36, v36, v123, v124
	v_max3_f32 v37, v37, v125, v126
	v_max3_f32 v36, v36, v127, v131
	v_max3_f32 v37, v37, v132, v133
	v_max3_f32 v36, v36, v134, v135
	v_max3_f32 v37, v37, v136, v137
	v_max3_f32 v36, v36, v138, v139
	v_max3_f32 v37, v37, v140, v141
	v_max3_f32 v36, v36, v142, v143
	v_max_f32_e32 v36, v36, v37
	v_mov_b32_e32 v37, v36
	s_nop 1
	v_permlane32_swap_b32_e32 v36, v37
	v_max_f32_e32 v36, v36, v37
	s_nop 0
	v_cmp_lt_f32_e32 vcc, s76, v36
	s_cbranch_vccz .Lfd_norescA
	v_max_f32_e32 v37, 0, v36
	v_add_f32_e32 v35, v35, v37
	v_sub_f32_e32 v112, v112, v37
	v_sub_f32_e32 v128, v128, v37
	v_sub_f32_e32 v113, v113, v37
	v_sub_f32_e32 v129, v129, v37
	v_sub_f32_e32 v114, v114, v37
	v_sub_f32_e32 v130, v130, v37
	v_sub_f32_e32 v115, v115, v37
	v_sub_f32_e32 v131, v131, v37
	v_sub_f32_e32 v116, v116, v37
	v_sub_f32_e32 v132, v132, v37
	v_sub_f32_e32 v117, v117, v37
	v_sub_f32_e32 v133, v133, v37
	v_sub_f32_e32 v118, v118, v37
	v_sub_f32_e32 v134, v134, v37
	v_sub_f32_e32 v119, v119, v37
	v_sub_f32_e32 v135, v135, v37
	v_sub_f32_e32 v120, v120, v37
	v_sub_f32_e32 v136, v136, v37
	v_sub_f32_e32 v121, v121, v37
	v_sub_f32_e32 v137, v137, v37
	v_sub_f32_e32 v122, v122, v37
	v_sub_f32_e32 v138, v138, v37
	v_sub_f32_e32 v123, v123, v37
	v_sub_f32_e32 v139, v139, v37
	v_sub_f32_e32 v124, v124, v37
	v_sub_f32_e32 v140, v140, v37
	v_sub_f32_e32 v125, v125, v37
	v_sub_f32_e32 v141, v141, v37
	v_sub_f32_e32 v126, v126, v37
	v_sub_f32_e32 v142, v142, v37
	v_sub_f32_e32 v127, v127, v37
	v_sub_f32_e32 v143, v143, v37
	v_sub_f32_e32 v144, 0, v35
	v_sub_f32_e32 v145, 0, v35
	v_sub_f32_e32 v146, 0, v35
	v_sub_f32_e32 v147, 0, v35
	v_sub_f32_e32 v148, 0, v35
	v_sub_f32_e32 v149, 0, v35
	v_sub_f32_e32 v150, 0, v35
	v_sub_f32_e32 v151, 0, v35
	v_sub_f32_e32 v152, 0, v35
	v_sub_f32_e32 v153, 0, v35
	v_sub_f32_e32 v154, 0, v35
	v_sub_f32_e32 v155, 0, v35
	v_sub_f32_e32 v156, 0, v35
	v_sub_f32_e32 v157, 0, v35
	v_sub_f32_e32 v158, 0, v35
	v_sub_f32_e32 v159, 0, v35
	v_sub_f32_e32 v38, 0, v37
	v_exp_f32_e32 v38, v38
	s_nop 0
	v_mul_f32_e32 v34, v34, v38
	s_waitcnt lgkmcnt(0)
	ds_write_b32 v44, v38
	s_waitcnt lgkmcnt(0)
	ds_read_b128 v[208:211], v45 offset:0
	ds_read_b128 v[212:215], v45 offset:32
	ds_read_b128 v[40:43], v45 offset:64
	ds_read_b128 v[6:9], v45 offset:96
	s_waitcnt lgkmcnt(0)
	v_mul_f32_e32 v48, v48, v208
	v_mul_f32_e32 v49, v49, v209
	v_mul_f32_e32 v50, v50, v210
	v_mul_f32_e32 v51, v51, v211
	v_mul_f32_e32 v52, v52, v212
	v_mul_f32_e32 v53, v53, v213
	v_mul_f32_e32 v54, v54, v214
	v_mul_f32_e32 v55, v55, v215
	v_mul_f32_e32 v56, v56, v40
	v_mul_f32_e32 v57, v57, v41
	v_mul_f32_e32 v58, v58, v42
	v_mul_f32_e32 v59, v59, v43
	v_mul_f32_e32 v60, v60, v6
	v_mul_f32_e32 v61, v61, v7
	v_mul_f32_e32 v62, v62, v8
	v_mul_f32_e32 v63, v63, v9
	v_mul_f32_e32 v64, v64, v208
	v_mul_f32_e32 v65, v65, v209
	v_mul_f32_e32 v66, v66, v210
	v_mul_f32_e32 v67, v67, v211
	v_mul_f32_e32 v68, v68, v212
	v_mul_f32_e32 v69, v69, v213
	v_mul_f32_e32 v70, v70, v214
	v_mul_f32_e32 v71, v71, v215
	v_mul_f32_e32 v72, v72, v40
	v_mul_f32_e32 v73, v73, v41
	v_mul_f32_e32 v74, v74, v42
	v_mul_f32_e32 v75, v75, v43
	v_mul_f32_e32 v76, v76, v6
	v_mul_f32_e32 v77, v77, v7
	v_mul_f32_e32 v78, v78, v8
	v_mul_f32_e32 v79, v79, v9
	v_mul_f32_e32 v80, v80, v208
	v_mul_f32_e32 v81, v81, v209
	v_mul_f32_e32 v82, v82, v210
	v_mul_f32_e32 v83, v83, v211
	v_mul_f32_e32 v84, v84, v212
	v_mul_f32_e32 v85, v85, v213
	v_mul_f32_e32 v86, v86, v214
	v_mul_f32_e32 v87, v87, v215
	v_mul_f32_e32 v88, v88, v40
	v_mul_f32_e32 v89, v89, v41
	v_mul_f32_e32 v90, v90, v42
	v_mul_f32_e32 v91, v91, v43
	v_mul_f32_e32 v92, v92, v6
	v_mul_f32_e32 v93, v93, v7
	v_mul_f32_e32 v94, v94, v8
	v_mul_f32_e32 v95, v95, v9
	v_mul_f32_e32 v96, v96, v208
	v_mul_f32_e32 v97, v97, v209
	v_mul_f32_e32 v98, v98, v210
	v_mul_f32_e32 v99, v99, v211
	v_mul_f32_e32 v100, v100, v212
	v_mul_f32_e32 v101, v101, v213
	v_mul_f32_e32 v102, v102, v214
	v_mul_f32_e32 v103, v103, v215
	v_mul_f32_e32 v104, v104, v40
	v_mul_f32_e32 v105, v105, v41
	v_mul_f32_e32 v106, v106, v42
	v_mul_f32_e32 v107, v107, v43
	v_mul_f32_e32 v108, v108, v6
	v_mul_f32_e32 v109, v109, v7
	v_mul_f32_e32 v110, v110, v8
	v_mul_f32_e32 v111, v111, v9
; __device__ __forceinline__ int crow(int r,int hi){return (r&3)+8*(r>>2)+4*hi;}
;     ...
;   {auto rr=__builtin_amdgcn_permlane32_swap(__float_as_uint(l_reg),__float_as_uint(l_reg),false,false);l_reg=__uint_as_float(rr[0])+__uint_as_float(rr[1]);}
;   if(hi==0)wsf[32+r32]=l_reg;asm volatile("s_waitcnt lgkmcnt(0)":::"memory");
;   float rli[16];
;   #pragma unroll
;   for(int r=0;r<16;++r)rli[r]=__builtin_amdgcn_rcpf(wsf[32+crow(r,hi)]);
.Lfd_norescA:
	v_exp_f32_e32 v112, v112
	v_exp_f32_e32 v113, v113
	v_exp_f32_e32 v114, v114
	v_exp_f32_e32 v115, v115
	v_exp_f32_e32 v116, v116
	v_exp_f32_e32 v117, v117
	v_exp_f32_e32 v118, v118
	v_exp_f32_e32 v119, v119
	v_cvt_pk_bf16_f32 v208, v112, v113
	v_cvt_pk_bf16_f32 v209, v114, v115
	v_cvt_pk_bf16_f32 v210, v116, v117
	v_cvt_pk_bf16_f32 v211, v118, v119
	v_mov_b32_e32 v4, 0
	v_mov_b32_e32 v5, 0
	s_waitcnt lgkmcnt(0)
	v_mfma_f32_32x32x16_bf16 v[80:95], v[208:211], v[220:223], v[80:95]
	v_exp_f32_e32 v120, v120
	v_exp_f32_e32 v121, v121
	v_exp_f32_e32 v122, v122
	v_add_f32_e32 v4, v112, v4
	v_mfma_f32_32x32x16_bf16 v[96:111], v[208:211], v[236:239], v[96:111]
	v_exp_f32_e32 v123, v123
	v_exp_f32_e32 v124, v124
	v_exp_f32_e32 v125, v125
	v_cvt_pk_bf16_f32 v212, v120, v121
	v_add_f32_e32 v5, v113, v5
	v_mfma_f32_32x32x16_bf16 v[48:63], v[208:211], v[176:179], v[48:63]
	v_exp_f32_e32 v126, v126
	v_exp_f32_e32 v127, v127
	v_cvt_pk_bf16_f32 v213, v122, v123
	v_cvt_pk_bf16_f32 v214, v124, v125
	v_add_f32_e32 v4, v114, v4
	v_add_f32_e32 v5, v115, v5
	v_mfma_f32_32x32x16_bf16 v[64:79], v[208:211], v[192:195], v[64:79]
	v_cvt_pk_bf16_f32 v215, v126, v127
	v_add_f32_e32 v4, v116, v4
	v_add_f32_e32 v5, v117, v5
	v_add_f32_e32 v4, v118, v4
	v_add_f32_e32 v5, v119, v5
	v_mfma_f32_32x32x16_bf16 v[80:95], v[212:215], v[224:227], v[80:95]
	v_exp_f32_e32 v128, v128
	v_exp_f32_e32 v129, v129
	v_exp_f32_e32 v130, v130
	v_add_f32_e32 v4, v120, v4
	v_mfma_f32_32x32x16_bf16 v[96:111], v[212:215], v[240:243], v[96:111]
	v_exp_f32_e32 v131, v131
	v_exp_f32_e32 v132, v132
	v_exp_f32_e32 v133, v133
	v_cvt_pk_bf16_f32 v40, v128, v129
	v_add_f32_e32 v5, v121, v5
	v_mfma_f32_32x32x16_bf16 v[48:63], v[212:215], v[180:183], v[48:63]
	v_exp_f32_e32 v134, v134
	v_exp_f32_e32 v135, v135
	v_cvt_pk_bf16_f32 v41, v130, v131
	v_cvt_pk_bf16_f32 v42, v132, v133
	v_add_f32_e32 v4, v122, v4
	v_add_f32_e32 v5, v123, v5
	v_mfma_f32_32x32x16_bf16 v[64:79], v[212:215], v[196:199], v[64:79]
	v_cvt_pk_bf16_f32 v43, v134, v135
	v_add_f32_e32 v4, v124, v4
	v_add_f32_e32 v5, v125, v5
	v_add_f32_e32 v4, v126, v4
	v_add_f32_e32 v5, v127, v5
	v_mfma_f32_32x32x16_bf16 v[80:95], v[40:43], v[228:231], v[80:95]
	v_exp_f32_e32 v136, v136
	v_exp_f32_e32 v137, v137
	v_exp_f32_e32 v138, v138
	v_add_f32_e32 v4, v128, v4
	v_mfma_f32_32x32x16_bf16 v[96:111], v[40:43], v[244:247], v[96:111]
	v_exp_f32_e32 v139, v139
	v_exp_f32_e32 v140, v140
	v_exp_f32_e32 v141, v141
	v_cvt_pk_bf16_f32 v6, v136, v137
	v_add_f32_e32 v5, v129, v5
	v_mfma_f32_32x32x16_bf16 v[48:63], v[40:43], v[184:187], v[48:63]
	v_exp_f32_e32 v142, v142
	v_exp_f32_e32 v143, v143
	v_cvt_pk_bf16_f32 v7, v138, v139
	v_cvt_pk_bf16_f32 v8, v140, v141
	v_add_f32_e32 v4, v130, v4
	v_add_f32_e32 v5, v131, v5
	v_mfma_f32_32x32x16_bf16 v[64:79], v[40:43], v[200:203], v[64:79]
	v_cvt_pk_bf16_f32 v9, v142, v143
	v_add_f32_e32 v4, v132, v4
	v_add_f32_e32 v5, v133, v5
	v_add_f32_e32 v4, v134, v4
	v_add_f32_e32 v5, v135, v5
	v_mfma_f32_32x32x16_bf16 v[80:95], v[6:9], v[232:235], v[80:95]
	v_add_f32_e32 v4, v136, v4
	v_mfma_f32_32x32x16_bf16 v[96:111], v[6:9], v[248:251], v[96:111]
	v_add_f32_e32 v5, v137, v5
	v_mfma_f32_32x32x16_bf16 v[48:63], v[6:9], v[188:191], v[48:63]
	v_add_f32_e32 v4, v138, v4
	v_add_f32_e32 v5, v139, v5
	v_mfma_f32_32x32x16_bf16 v[64:79], v[6:9], v[204:207], v[64:79]
	v_add_f32_e32 v4, v140, v4
	v_add_f32_e32 v5, v141, v5
	v_add_f32_e32 v4, v142, v4
	v_add_f32_e32 v5, v143, v5
	v_add_f32_e32 v4, v4, v5
	v_add_f32_e32 v34, v34, v4
	s_branch .Lfd_next
.Lfd_next:
	s_add_i32 s88, s88, 1
	s_cmp_lt_i32 s88, s89
	s_cbranch_scc1 .Lfd_loop
	s_waitcnt vmcnt(0)
	s_barrier
	s_nop 7
	s_nop 7
	v_mov_b32_e32 v4, v34
	v_mov_b32_e32 v5, v34
	s_nop 1
	v_permlane32_swap_b32_e32 v4, v5
	v_add_f32_e32 v4, v4, v5
	ds_write_b32 v44, v4 offset:128
	s_waitcnt lgkmcnt(0)
	ds_read_b128 v[112:115], v45 offset:128
	ds_read_b128 v[116:119], v45 offset:160
	ds_read_b128 v[120:123], v45 offset:192
	ds_read_b128 v[124:127], v45 offset:224
	s_waitcnt lgkmcnt(0)
	v_rcp_f32_e32 v112, v112
	v_rcp_f32_e32 v113, v113
	v_rcp_f32_e32 v114, v114
	v_rcp_f32_e32 v115, v115
	v_rcp_f32_e32 v116, v116
	v_rcp_f32_e32 v117, v117
	v_rcp_f32_e32 v118, v118
	v_rcp_f32_e32 v119, v119
	v_rcp_f32_e32 v120, v120
	v_rcp_f32_e32 v121, v121
	v_rcp_f32_e32 v122, v122
	v_rcp_f32_e32 v123, v123
	v_rcp_f32_e32 v124, v124
	v_rcp_f32_e32 v125, v125
	v_rcp_f32_e32 v126, v126
	v_rcp_f32_e32 v127, v127
	s_nop 0
	s_cmp_lg_u32 s90, 0
	s_cbranch_scc1 .Lfd_epi1
; __device__ __forceinline__ unsigned cvtpk_s(float lo,float hi){f32x2_t v={lo,hi};bf16x2_t b=__builtin_convertvector(v,bf16x2_t);return __builtin_bit_cast(unsigned,b);}
; #define ATTN_STORE16(p,v) st16_wt((p),(v))
;     ...
;       #pragma unroll
;       for(int r=0;r<16;++r){
;         #pragma unroll
;         for(int d0=0;d0<2;++d0)stl[cr0(r)*64+d0*32]=(bf16)(cvtpk_s(o[d0][r]*rli[r],0.f)&0xffffu);}
;     }
;     asm volatile("s_waitcnt lgkmcnt(0)":::"memory");
;     if(emode==0){
;       #pragma unroll
;       for(int i=0;i<4;++i){const int row=i*8+(lane>>3),ch=lane&7; const u32x4 v=*(const u32x4*)(stg+row*64+ch*8); ATTN_STORE16(Ow+(long)row*OP+ch*8,v);}
	v_mul_f32_e32 v4, v48, v112
	v_cvt_pk_bf16_f32 v4, v4, v4
	ds_write_b16 v46, v4 offset:0
	v_mul_f32_e32 v4, v49, v113
	v_cvt_pk_bf16_f32 v4, v4, v4
	ds_write_b16 v46, v4 offset:256
	v_mul_f32_e32 v4, v50, v114
	v_cvt_pk_bf16_f32 v4, v4, v4
	ds_write_b16 v46, v4 offset:512
	v_mul_f32_e32 v4, v51, v115
	v_cvt_pk_bf16_f32 v4, v4, v4
	ds_write_b16 v46, v4 offset:768
	v_mul_f32_e32 v4, v52, v116
	v_cvt_pk_bf16_f32 v4, v4, v4
	ds_write_b16 v46, v4 offset:2048
	v_mul_f32_e32 v4, v53, v117
	v_cvt_pk_bf16_f32 v4, v4, v4
	ds_write_b16 v46, v4 offset:2304
	v_mul_f32_e32 v4, v54, v118
	v_cvt_pk_bf16_f32 v4, v4, v4
	ds_write_b16 v46, v4 offset:2560
	v_mul_f32_e32 v4, v55, v119
	v_cvt_pk_bf16_f32 v4, v4, v4
	ds_write_b16 v46, v4 offset:2816
	v_mul_f32_e32 v4, v56, v120
	v_cvt_pk_bf16_f32 v4, v4, v4
	ds_write_b16 v46, v4 offset:4096
	v_mul_f32_e32 v4, v57, v121
	v_cvt_pk_bf16_f32 v4, v4, v4
	ds_write_b16 v46, v4 offset:4352
	v_mul_f32_e32 v4, v58, v122
	v_cvt_pk_bf16_f32 v4, v4, v4
	ds_write_b16 v46, v4 offset:4608
	v_mul_f32_e32 v4, v59, v123
	v_cvt_pk_bf16_f32 v4, v4, v4
	ds_write_b16 v46, v4 offset:4864
	v_mul_f32_e32 v4, v60, v124
	v_cvt_pk_bf16_f32 v4, v4, v4
	ds_write_b16 v46, v4 offset:6144
	v_mul_f32_e32 v4, v61, v125
	v_cvt_pk_bf16_f32 v4, v4, v4
	ds_write_b16 v46, v4 offset:6400
	v_mul_f32_e32 v4, v62, v126
	v_cvt_pk_bf16_f32 v4, v4, v4
	ds_write_b16 v46, v4 offset:6656
	v_mul_f32_e32 v4, v63, v127
	v_cvt_pk_bf16_f32 v4, v4, v4
	ds_write_b16 v46, v4 offset:6912
	v_mul_f32_e32 v4, v64, v112
	v_cvt_pk_bf16_f32 v4, v4, v4
	ds_write_b16 v46, v4 offset:64
	v_mul_f32_e32 v4, v65, v113
	v_cvt_pk_bf16_f32 v4, v4, v4
	ds_write_b16 v46, v4 offset:320
	v_mul_f32_e32 v4, v66, v114
	v_cvt_pk_bf16_f32 v4, v4, v4
	ds_write_b16 v46, v4 offset:576
	v_mul_f32_e32 v4, v67, v115
	v_cvt_pk_bf16_f32 v4, v4, v4
	ds_write_b16 v46, v4 offset:832
	v_mul_f32_e32 v4, v68, v116
	v_cvt_pk_bf16_f32 v4, v4, v4
	ds_write_b16 v46, v4 offset:2112
	v_mul_f32_e32 v4, v69, v117
	v_cvt_pk_bf16_f32 v4, v4, v4
	ds_write_b16 v46, v4 offset:2368
	v_mul_f32_e32 v4, v70, v118
	v_cvt_pk_bf16_f32 v4, v4, v4
	ds_write_b16 v46, v4 offset:2624
	v_mul_f32_e32 v4, v71, v119
	v_cvt_pk_bf16_f32 v4, v4, v4
	ds_write_b16 v46, v4 offset:2880
	v_mul_f32_e32 v4, v72, v120
	v_cvt_pk_bf16_f32 v4, v4, v4
	ds_write_b16 v46, v4 offset:4160
	v_mul_f32_e32 v4, v73, v121
	v_cvt_pk_bf16_f32 v4, v4, v4
	ds_write_b16 v46, v4 offset:4416
	v_mul_f32_e32 v4, v74, v122
	v_cvt_pk_bf16_f32 v4, v4, v4
	ds_write_b16 v46, v4 offset:4672
	v_mul_f32_e32 v4, v75, v123
	v_cvt_pk_bf16_f32 v4, v4, v4
	ds_write_b16 v46, v4 offset:4928
	v_mul_f32_e32 v4, v76, v124
	v_cvt_pk_bf16_f32 v4, v4, v4
	ds_write_b16 v46, v4 offset:6208
	v_mul_f32_e32 v4, v77, v125
	v_cvt_pk_bf16_f32 v4, v4, v4
	ds_write_b16 v46, v4 offset:6464
	v_mul_f32_e32 v4, v78, v126
	v_cvt_pk_bf16_f32 v4, v4, v4
	ds_write_b16 v46, v4 offset:6720
	v_mul_f32_e32 v4, v79, v127
	v_cvt_pk_bf16_f32 v4, v4, v4
	ds_write_b16 v46, v4 offset:6976
	v_mul_f32_e32 v4, v80, v112
	v_cvt_pk_bf16_f32 v4, v4, v4
	ds_write_b16 v46, v4 offset:128
	v_mul_f32_e32 v4, v81, v113
	v_cvt_pk_bf16_f32 v4, v4, v4
	ds_write_b16 v46, v4 offset:384
	v_mul_f32_e32 v4, v82, v114
	v_cvt_pk_bf16_f32 v4, v4, v4
	ds_write_b16 v46, v4 offset:640
	v_mul_f32_e32 v4, v83, v115
	v_cvt_pk_bf16_f32 v4, v4, v4
	ds_write_b16 v46, v4 offset:896
	v_mul_f32_e32 v4, v84, v116
	v_cvt_pk_bf16_f32 v4, v4, v4
	ds_write_b16 v46, v4 offset:2176
	v_mul_f32_e32 v4, v85, v117
	v_cvt_pk_bf16_f32 v4, v4, v4
	ds_write_b16 v46, v4 offset:2432
	v_mul_f32_e32 v4, v86, v118
	v_cvt_pk_bf16_f32 v4, v4, v4
	ds_write_b16 v46, v4 offset:2688
	v_mul_f32_e32 v4, v87, v119
	v_cvt_pk_bf16_f32 v4, v4, v4
	ds_write_b16 v46, v4 offset:2944
	v_mul_f32_e32 v4, v88, v120
	v_cvt_pk_bf16_f32 v4, v4, v4
	ds_write_b16 v46, v4 offset:4224
	v_mul_f32_e32 v4, v89, v121
	v_cvt_pk_bf16_f32 v4, v4, v4
	ds_write_b16 v46, v4 offset:4480
	v_mul_f32_e32 v4, v90, v122
	v_cvt_pk_bf16_f32 v4, v4, v4
	ds_write_b16 v46, v4 offset:4736
	v_mul_f32_e32 v4, v91, v123
	v_cvt_pk_bf16_f32 v4, v4, v4
	ds_write_b16 v46, v4 offset:4992
	v_mul_f32_e32 v4, v92, v124
	v_cvt_pk_bf16_f32 v4, v4, v4
	ds_write_b16 v46, v4 offset:6272
	v_mul_f32_e32 v4, v93, v125
	v_cvt_pk_bf16_f32 v4, v4, v4
	ds_write_b16 v46, v4 offset:6528
	v_mul_f32_e32 v4, v94, v126
	v_cvt_pk_bf16_f32 v4, v4, v4
	ds_write_b16 v46, v4 offset:6784
	v_mul_f32_e32 v4, v95, v127
	v_cvt_pk_bf16_f32 v4, v4, v4
	ds_write_b16 v46, v4 offset:7040
	v_mul_f32_e32 v4, v96, v112
	v_cvt_pk_bf16_f32 v4, v4, v4
	ds_write_b16 v46, v4 offset:192
	v_mul_f32_e32 v4, v97, v113
	v_cvt_pk_bf16_f32 v4, v4, v4
	ds_write_b16 v46, v4 offset:448
	v_mul_f32_e32 v4, v98, v114
	v_cvt_pk_bf16_f32 v4, v4, v4
	ds_write_b16 v46, v4 offset:704
	v_mul_f32_e32 v4, v99, v115
	v_cvt_pk_bf16_f32 v4, v4, v4
	ds_write_b16 v46, v4 offset:960
	v_mul_f32_e32 v4, v100, v116
	v_cvt_pk_bf16_f32 v4, v4, v4
	ds_write_b16 v46, v4 offset:2240
	v_mul_f32_e32 v4, v101, v117
	v_cvt_pk_bf16_f32 v4, v4, v4
	ds_write_b16 v46, v4 offset:2496
	v_mul_f32_e32 v4, v102, v118
	v_cvt_pk_bf16_f32 v4, v4, v4
	ds_write_b16 v46, v4 offset:2752
	v_mul_f32_e32 v4, v103, v119
	v_cvt_pk_bf16_f32 v4, v4, v4
	ds_write_b16 v46, v4 offset:3008
	v_mul_f32_e32 v4, v104, v120
	v_cvt_pk_bf16_f32 v4, v4, v4
	ds_write_b16 v46, v4 offset:4288
	v_mul_f32_e32 v4, v105, v121
	v_cvt_pk_bf16_f32 v4, v4, v4
	ds_write_b16 v46, v4 offset:4544
	v_mul_f32_e32 v4, v106, v122
	v_cvt_pk_bf16_f32 v4, v4, v4
	ds_write_b16 v46, v4 offset:4800
	v_mul_f32_e32 v4, v107, v123
	v_cvt_pk_bf16_f32 v4, v4, v4
	ds_write_b16 v46, v4 offset:5056
	v_mul_f32_e32 v4, v108, v124
	v_cvt_pk_bf16_f32 v4, v4, v4
	ds_write_b16 v46, v4 offset:6336
	v_mul_f32_e32 v4, v109, v125
	v_cvt_pk_bf16_f32 v4, v4, v4
	ds_write_b16 v46, v4 offset:6592
	v_mul_f32_e32 v4, v110, v126
	v_cvt_pk_bf16_f32 v4, v4, v4
	ds_write_b16 v46, v4 offset:6848
	v_mul_f32_e32 v4, v111, v127
	v_cvt_pk_bf16_f32 v4, v4, v4
	ds_write_b16 v46, v4 offset:7104
	s_waitcnt lgkmcnt(0)
	ds_read_b128 v[176:179], v219 offset:0
	ds_read_b128 v[180:183], v219 offset:1024
	ds_read_b128 v[184:187], v219 offset:2048
	ds_read_b128 v[188:191], v219 offset:3072
	ds_read_b128 v[192:195], v219 offset:4096
	ds_read_b128 v[196:199], v219 offset:5120
	ds_read_b128 v[200:203], v219 offset:6144
	ds_read_b128 v[204:207], v219 offset:7168
	s_waitcnt lgkmcnt(0)
	v_mov_b32_e32 v253, v252
	global_store_dwordx4 v253, v[176:179], s[86:87]
	v_add_u32_e32 v253, 0x2000, v253
	global_store_dwordx4 v253, v[180:183], s[86:87]
	v_add_u32_e32 v253, 0x2000, v253
	global_store_dwordx4 v253, v[184:187], s[86:87]
	v_add_u32_e32 v253, 0x2000, v253
	global_store_dwordx4 v253, v[188:191], s[86:87]
	v_add_u32_e32 v253, 0x2000, v253
	global_store_dwordx4 v253, v[192:195], s[86:87]
	v_add_u32_e32 v253, 0x2000, v253
	global_store_dwordx4 v253, v[196:199], s[86:87]
	v_add_u32_e32 v253, 0x2000, v253
	global_store_dwordx4 v253, v[200:203], s[86:87]
	v_add_u32_e32 v253, 0x2000, v253
	global_store_dwordx4 v253, v[204:207], s[86:87]
	s_waitcnt vmcnt(0)
	s_barrier
; __device__ __forceinline__ void run(Frame& F, int qword) {
;     ...
;             for (int sp = 0; sp < 4; ++sp) {
;                 const int c = sp >> 1, vh = sp & 1;
;                 attn_body::attn_unit<8, false>(qb, QB + rq * 512 + (h * 2 + c) * 64, 512, KB + r0 * 512 + (h * 2 + c) * 64, 512, VB + r0 * 512 + h * 128 + vh * 64, 512,
;                                                ATT + rq * 1024 + 512 + h * 128, 1024, nullptr, shm, F.wave, sp < 2 ? 1 : (sp == 2 ? 2 : 3), vh, lam);
	s_mov_b32 s90, 1
	s_branch .Lfd_pass
